# row-scale table build: closed-form tile rows instead of 16-iteration scan, both rows built concurrently (5 GEMM phases); plus peel + ssm2
# speedup vs baseline: 1.0157x; 1.0027x over previous
.LBB0_196:
	s_cmp_lt_i32 s30, 2
	s_cselect_b64 s[4:5], -1, 0
	s_add_u32 s36, s28, 0x6800000
	s_addc_u32 s37, s29, 0
	s_add_u32 s40, s28, 0xa800000
	s_addc_u32 s41, s29, 0
	s_and_b64 s[6:7], s[4:5], s[0:1]
	s_andn2_b64 vcc, exec, s[6:7]
	s_cbranch_vccnz .LBB0_231
	s_ashr_i32 s3, s2, 31
	s_ashr_i32 s48, s22, 31
	s_mov_b32 s49, s22
	s_mov_b32 s50, -1
	s_mov_b32 s4, 16
	v_mov_b64_e32 v[0:1], 0xaff
	s_mov_b64 s[0:1], s[2:3]
	s_mov_b32 s52, -1
	s_mov_b32 s51, -1
	s_mov_b32 s12, -1
	s_and_b32 s5, s2, 7
	s_lshl_b32 s5, s5, 4
	s_bfe_u32 s8, s2, 0x30003
	s_add_i32 s50, s5, s8
	s_add_i32 s52, s50, 8
.LBB0_207:
	s_add_u32 s8, s28, 0x5800000
	s_movk_i32 s0, 0x100
	s_addc_u32 s9, s29, 0
	v_cmp_gt_u32_e64 s[4:5], s0, v197
	s_add_i32 s0, 0, 0x20000
	s_cmp_gt_i32 s50, -1
	v_lshl_add_u32 v0, v197, 2, s0
	s_cselect_b64 s[0:1], -1, 0
	s_and_b64 s[0:1], s[0:1], exec
	s_waitcnt lgkmcnt(0)
	s_barrier
	s_and_saveexec_b64 s[10:11], s[0:1]
	s_cbranch_execz .LBB0_209
	v_mov_b32_e32 v30, s50
	v_mov_b32_e32 v31, s52
	v_cmp_lt_u32_e32 vcc, 0xff, v197
	v_and_b32_e32 v2, 0xff, v197
	s_nop 0
	v_cndmask_b32_e32 v30, v30, v31, vcc
	v_lshl_or_b32 v2, v30, 8, v2
	v_mov_b32_e32 v3, 0
	v_add_u32_e32 v18, 0x38000, v2
	v_mov_b32_e32 v19, v3
	v_lshl_add_u64 v[4:5], v[2:3], 2, s[8:9]
	v_add_u32_e32 v6, 0x8000, v2
	v_mov_b32_e32 v7, v3
	v_add_u32_e32 v8, 0x10000, v2
	v_mov_b32_e32 v9, v3
	v_add_u32_e32 v10, 0x18000, v2
	v_mov_b32_e32 v11, v3
	v_add_u32_e32 v12, 0x20000, v2
	v_mov_b32_e32 v13, v3
	v_add_u32_e32 v14, 0x28000, v2
	v_mov_b32_e32 v15, v3
	v_add_u32_e32 v16, 0x30000, v2
	v_mov_b32_e32 v17, v3
	v_lshl_add_u64 v[18:19], v[18:19], 2, s[8:9]
	v_lshl_add_u64 v[6:7], v[6:7], 2, s[8:9]
	v_lshl_add_u64 v[8:9], v[8:9], 2, s[8:9]
	v_lshl_add_u64 v[10:11], v[10:11], 2, s[8:9]
	v_lshl_add_u64 v[12:13], v[12:13], 2, s[8:9]
	v_lshl_add_u64 v[14:15], v[14:15], 2, s[8:9]
	v_lshl_add_u64 v[16:17], v[16:17], 2, s[8:9]
	global_load_dword v1, v[4:5], off
	global_load_dword v20, v[6:7], off
	global_load_dword v21, v[8:9], off
	global_load_dword v22, v[10:11], off
	global_load_dword v23, v[12:13], off
	global_load_dword v24, v[14:15], off
	global_load_dword v25, v[16:17], off
	s_nop 0
	global_load_dword v18, v[18:19], off
	v_add_u32_e32 v4, 0x40000, v2
	v_mov_b32_e32 v5, v3
	v_add_u32_e32 v6, 0x48000, v2
	v_mov_b32_e32 v7, v3
	v_add_u32_e32 v8, 0x50000, v2
	v_mov_b32_e32 v9, v3
	v_add_u32_e32 v10, 0x58000, v2
	v_mov_b32_e32 v11, v3
	v_add_u32_e32 v12, 0x60000, v2
	v_add_u32_e32 v14, 0x68000, v2
	v_add_u32_e32 v16, 0x70000, v2
	v_add_u32_e32 v2, 0x78000, v2
	v_lshl_add_u64 v[4:5], v[4:5], 2, s[8:9]
	v_lshl_add_u64 v[6:7], v[6:7], 2, s[8:9]
	v_lshl_add_u64 v[8:9], v[8:9], 2, s[8:9]
	v_lshl_add_u64 v[10:11], v[10:11], 2, s[8:9]
	v_mov_b32_e32 v13, v3
	v_mov_b32_e32 v15, v3
	v_mov_b32_e32 v17, v3
	v_lshl_add_u64 v[2:3], v[2:3], 2, s[8:9]
	v_lshl_add_u64 v[12:13], v[12:13], 2, s[8:9]
	v_lshl_add_u64 v[14:15], v[14:15], 2, s[8:9]
	v_lshl_add_u64 v[16:17], v[16:17], 2, s[8:9]
	global_load_dword v4, v[4:5], off
	s_nop 0
	global_load_dword v5, v[6:7], off
	s_nop 0
	global_load_dword v6, v[8:9], off
	global_load_dword v7, v[10:11], off
	s_nop 0
	global_load_dword v8, v[12:13], off
	global_load_dword v9, v[14:15], off
	global_load_dword v10, v[16:17], off
	s_nop 0
	global_load_dword v2, v[2:3], off
	v_mov_b32_e32 v3, 0x358637bd
	s_mov_b32 s0, 0xf800000
	s_waitcnt vmcnt(15)
	v_add_f32_e32 v1, 0, v1
	s_waitcnt vmcnt(14)
	v_add_f32_e32 v1, v1, v20
	s_waitcnt vmcnt(13)
	v_add_f32_e32 v1, v1, v21
	s_waitcnt vmcnt(12)
	v_add_f32_e32 v1, v1, v22
	s_waitcnt vmcnt(11)
	v_add_f32_e32 v1, v1, v23
	s_waitcnt vmcnt(10)
	v_add_f32_e32 v1, v1, v24
	s_waitcnt vmcnt(9)
	v_add_f32_e32 v1, v1, v25
	s_waitcnt vmcnt(8)
	v_add_f32_e32 v1, v1, v18
	s_waitcnt vmcnt(7)
	v_add_f32_e32 v1, v1, v4
	s_waitcnt vmcnt(6)
	v_add_f32_e32 v1, v1, v5
	s_waitcnt vmcnt(5)
	v_add_f32_e32 v1, v1, v6
	s_waitcnt vmcnt(4)
	v_add_f32_e32 v1, v1, v7
	s_waitcnt vmcnt(3)
	v_add_f32_e32 v1, v1, v8
	s_waitcnt vmcnt(2)
	v_add_f32_e32 v1, v1, v9
	s_waitcnt vmcnt(1)
	v_add_f32_e32 v1, v1, v10
	s_waitcnt vmcnt(0)
	v_add_f32_e32 v1, v1, v2
	v_fmac_f32_e32 v3, 0x3a800000, v1
	v_mul_f32_e32 v1, 0x4f800000, v3
	v_cmp_gt_f32_e32 vcc, s0, v3
	s_nop 1
	v_cndmask_b32_e32 v1, v3, v1, vcc
	v_sqrt_f32_e32 v2, v1
	v_mov_b32_e32 v3, 0x260
	v_add_u32_e32 v4, -1, v2
	v_add_u32_e32 v5, 1, v2
	v_fma_f32 v6, -v4, v2, v1
	v_fma_f32 v7, -v5, v2, v1
	v_cmp_ge_f32_e64 s[0:1], 0, v6
	s_nop 1
	v_cndmask_b32_e64 v2, v2, v4, s[0:1]
	v_cmp_lt_f32_e64 s[0:1], 0, v7
	s_nop 1
	v_cndmask_b32_e64 v2, v2, v5, s[0:1]
	v_mul_f32_e32 v4, 0x37800000, v2
	v_cndmask_b32_e32 v2, v2, v4, vcc
	v_cmp_class_f32_e32 vcc, v1, v3
	s_nop 1
	v_cndmask_b32_e32 v1, v2, v1, vcc
	v_div_scale_f32 v2, s[0:1], v1, v1, 1.0
	v_rcp_f32_e32 v3, v2
	v_div_scale_f32 v4, vcc, 1.0, v1, 1.0
	v_fma_f32 v5, -v2, v3, 1.0
	v_fmac_f32_e32 v3, v5, v3
	v_mul_f32_e32 v5, v4, v3
	v_fma_f32 v6, -v2, v5, v4
	v_fmac_f32_e32 v5, v6, v3
	v_fma_f32 v2, -v2, v5, v4
	v_div_fmas_f32 v2, v2, v3, v5
	v_div_fixup_f32 v1, v2, v1, 1.0
	ds_write_b32 v0, v1
.LBB0_209:
	s_or_b64 exec, exec, s[10:11]
	s_cmp_lg_u32 s52, s52
	s_cselect_b64 s[0:1], -1, 0
	s_and_b64 s[0:1], s[0:1], s[4:5]
	s_and_saveexec_b64 s[10:11], s[0:1]
	s_cbranch_execz .LBB0_211
	v_lshl_or_b32 v2, s52, 8, v197
	v_mov_b32_e32 v3, 0
	v_add_u32_e32 v18, 0x38000, v2
	v_mov_b32_e32 v19, v3
	v_lshl_add_u64 v[4:5], v[2:3], 2, s[8:9]
	v_add_u32_e32 v6, 0x8000, v2
	v_mov_b32_e32 v7, v3
	v_add_u32_e32 v8, 0x10000, v2
	v_mov_b32_e32 v9, v3
	v_add_u32_e32 v10, 0x18000, v2
	v_mov_b32_e32 v11, v3
	v_add_u32_e32 v12, 0x20000, v2
	v_mov_b32_e32 v13, v3
	v_add_u32_e32 v14, 0x28000, v2
	v_mov_b32_e32 v15, v3
	v_add_u32_e32 v16, 0x30000, v2
	v_mov_b32_e32 v17, v3
	v_lshl_add_u64 v[18:19], v[18:19], 2, s[8:9]
	v_lshl_add_u64 v[6:7], v[6:7], 2, s[8:9]
	v_lshl_add_u64 v[8:9], v[8:9], 2, s[8:9]
	v_lshl_add_u64 v[10:11], v[10:11], 2, s[8:9]
	v_lshl_add_u64 v[12:13], v[12:13], 2, s[8:9]
	v_lshl_add_u64 v[14:15], v[14:15], 2, s[8:9]
	v_lshl_add_u64 v[16:17], v[16:17], 2, s[8:9]
	global_load_dword v1, v[4:5], off
	global_load_dword v20, v[6:7], off
	global_load_dword v21, v[8:9], off
	global_load_dword v22, v[10:11], off
	global_load_dword v23, v[12:13], off
	global_load_dword v24, v[14:15], off
	global_load_dword v25, v[16:17], off
	s_nop 0
	global_load_dword v18, v[18:19], off
	v_add_u32_e32 v4, 0x40000, v2
	v_mov_b32_e32 v5, v3
	v_add_u32_e32 v6, 0x48000, v2
	v_mov_b32_e32 v7, v3
	v_add_u32_e32 v8, 0x50000, v2
	v_mov_b32_e32 v9, v3
	v_add_u32_e32 v10, 0x58000, v2
	v_mov_b32_e32 v11, v3
	v_add_u32_e32 v12, 0x60000, v2
	v_add_u32_e32 v14, 0x68000, v2
	v_add_u32_e32 v16, 0x70000, v2
	v_add_u32_e32 v2, 0x78000, v2
	v_lshl_add_u64 v[4:5], v[4:5], 2, s[8:9]
	v_lshl_add_u64 v[6:7], v[6:7], 2, s[8:9]
	v_lshl_add_u64 v[8:9], v[8:9], 2, s[8:9]
	v_lshl_add_u64 v[10:11], v[10:11], 2, s[8:9]
	v_mov_b32_e32 v13, v3
	v_mov_b32_e32 v15, v3
	v_mov_b32_e32 v17, v3
	v_lshl_add_u64 v[2:3], v[2:3], 2, s[8:9]
	v_lshl_add_u64 v[12:13], v[12:13], 2, s[8:9]
	v_lshl_add_u64 v[14:15], v[14:15], 2, s[8:9]
	v_lshl_add_u64 v[16:17], v[16:17], 2, s[8:9]
	global_load_dword v4, v[4:5], off
	s_nop 0
	global_load_dword v5, v[6:7], off
	s_nop 0
	global_load_dword v6, v[8:9], off
	global_load_dword v7, v[10:11], off
	s_nop 0
	global_load_dword v8, v[12:13], off
	global_load_dword v9, v[14:15], off
	global_load_dword v10, v[16:17], off
	s_nop 0
	global_load_dword v2, v[2:3], off
	v_mov_b32_e32 v3, 0x358637bd
	s_mov_b32 s0, 0xf800000
	s_waitcnt vmcnt(15)
	v_add_f32_e32 v1, 0, v1
	s_waitcnt vmcnt(14)
	v_add_f32_e32 v1, v1, v20
	s_waitcnt vmcnt(13)
	v_add_f32_e32 v1, v1, v21
	s_waitcnt vmcnt(12)
	v_add_f32_e32 v1, v1, v22
	s_waitcnt vmcnt(11)
	v_add_f32_e32 v1, v1, v23
	s_waitcnt vmcnt(10)
	v_add_f32_e32 v1, v1, v24
	s_waitcnt vmcnt(9)
	v_add_f32_e32 v1, v1, v25
	s_waitcnt vmcnt(8)
	v_add_f32_e32 v1, v1, v18
	s_waitcnt vmcnt(7)
	v_add_f32_e32 v1, v1, v4
	s_waitcnt vmcnt(6)
	v_add_f32_e32 v1, v1, v5
	s_waitcnt vmcnt(5)
	v_add_f32_e32 v1, v1, v6
	s_waitcnt vmcnt(4)
	v_add_f32_e32 v1, v1, v7
	s_waitcnt vmcnt(3)
	v_add_f32_e32 v1, v1, v8
	s_waitcnt vmcnt(2)
	v_add_f32_e32 v1, v1, v9
	s_waitcnt vmcnt(1)
	v_add_f32_e32 v1, v1, v10
	s_waitcnt vmcnt(0)
	v_add_f32_e32 v1, v1, v2
	v_fmac_f32_e32 v3, 0x3a800000, v1
	v_mul_f32_e32 v1, 0x4f800000, v3
	v_cmp_gt_f32_e32 vcc, s0, v3
	s_nop 1
	v_cndmask_b32_e32 v1, v3, v1, vcc
	v_sqrt_f32_e32 v2, v1
	v_mov_b32_e32 v3, 0x260
	v_add_u32_e32 v4, -1, v2
	v_add_u32_e32 v5, 1, v2
	v_fma_f32 v6, -v4, v2, v1
	v_fma_f32 v7, -v5, v2, v1
	v_cmp_ge_f32_e64 s[0:1], 0, v6
	s_nop 1
	v_cndmask_b32_e64 v2, v2, v4, s[0:1]
	v_cmp_lt_f32_e64 s[0:1], 0, v7
	s_nop 1
	v_cndmask_b32_e64 v2, v2, v5, s[0:1]
	v_mul_f32_e32 v4, 0x37800000, v2
	v_cndmask_b32_e32 v2, v2, v4, vcc
	v_cmp_class_f32_e32 vcc, v1, v3
	s_nop 1
	v_cndmask_b32_e32 v1, v2, v1, vcc
	v_div_scale_f32 v2, s[0:1], v1, v1, 1.0
	v_rcp_f32_e32 v3, v2
	v_div_scale_f32 v4, vcc, 1.0, v1, 1.0
	v_fma_f32 v5, -v2, v3, 1.0
	v_fmac_f32_e32 v3, v5, v3
	v_mul_f32_e32 v5, v4, v3
	v_fma_f32 v6, -v2, v5, v4
	v_fmac_f32_e32 v5, v6, v3
	v_fma_f32 v2, -v2, v5, v4
	v_div_fmas_f32 v2, v2, v3, v5
	v_div_fixup_f32 v1, v2, v1, 1.0
	ds_write_b32 v0, v1 offset:1024

.LBB0_386:
	s_cmp_lt_i32 s30, 4
	s_cselect_b64 s[4:5], -1, 0
	s_add_u32 s46, s28, 0xc800000
	s_addc_u32 s47, s29, 0
	s_and_b64 s[6:7], s[4:5], s[0:1]
	s_andn2_b64 vcc, exec, s[6:7]
	s_cbranch_vccnz .LBB0_425
	s_ashr_i32 s3, s2, 31
	s_ashr_i32 s56, s22, 31
	s_mov_b32 s57, s22
	s_mov_b32 s58, -1
	s_mov_b32 s4, 16
	s_waitcnt lgkmcnt(0)
	v_mov_b64_e32 v[0:1], 0x2ff
	s_mov_b64 s[0:1], s[2:3]
	s_mov_b32 s60, -1
	s_mov_b32 s59, -1
	s_mov_b32 s12, -1
	s_and_b32 s5, s2, 7
	s_lshl_b32 s5, s5, 4
	s_bfe_u32 s8, s2, 0x30003
	s_add_i32 s58, s5, s8
	s_add_i32 s60, s58, 8
.LBB0_397:
	s_add_u32 s8, s28, 0x5a00000
	s_movk_i32 s0, 0x100
	s_addc_u32 s9, s29, 0
	v_cmp_gt_u32_e64 s[4:5], s0, v197
	s_add_i32 s0, 0, 0x20000
	s_cmp_gt_i32 s58, -1
	v_lshl_add_u32 v0, v197, 2, s0
	s_cselect_b64 s[0:1], -1, 0
	s_and_b64 s[0:1], s[0:1], exec
	s_waitcnt vmcnt(0)
	s_barrier
	s_and_saveexec_b64 s[10:11], s[0:1]
	s_cbranch_execz .LBB0_399
	v_mov_b32_e32 v30, s58
	v_mov_b32_e32 v31, s60
	v_cmp_lt_u32_e32 vcc, 0xff, v197
	v_and_b32_e32 v2, 0xff, v197
	s_nop 0
	v_cndmask_b32_e32 v30, v30, v31, vcc
	v_lshl_or_b32 v2, v30, 8, v2
	v_mov_b32_e32 v3, 0
	v_add_u32_e32 v18, 0x38000, v2
	v_mov_b32_e32 v19, v3
	v_lshl_add_u64 v[4:5], v[2:3], 2, s[8:9]
	v_add_u32_e32 v6, 0x8000, v2
	v_mov_b32_e32 v7, v3
	v_add_u32_e32 v8, 0x10000, v2
	v_mov_b32_e32 v9, v3
	v_add_u32_e32 v10, 0x18000, v2
	v_mov_b32_e32 v11, v3
	v_add_u32_e32 v12, 0x20000, v2
	v_mov_b32_e32 v13, v3
	v_add_u32_e32 v14, 0x28000, v2
	v_mov_b32_e32 v15, v3
	v_add_u32_e32 v16, 0x30000, v2
	v_mov_b32_e32 v17, v3
	v_lshl_add_u64 v[18:19], v[18:19], 2, s[8:9]
	v_lshl_add_u64 v[6:7], v[6:7], 2, s[8:9]
	v_lshl_add_u64 v[8:9], v[8:9], 2, s[8:9]
	v_lshl_add_u64 v[10:11], v[10:11], 2, s[8:9]
	v_lshl_add_u64 v[12:13], v[12:13], 2, s[8:9]
	v_lshl_add_u64 v[14:15], v[14:15], 2, s[8:9]
	v_lshl_add_u64 v[16:17], v[16:17], 2, s[8:9]
	global_load_dword v1, v[4:5], off
	global_load_dword v20, v[6:7], off
	global_load_dword v21, v[8:9], off
	global_load_dword v22, v[10:11], off
	global_load_dword v23, v[12:13], off
	global_load_dword v24, v[14:15], off
	global_load_dword v25, v[16:17], off
	s_nop 0
	global_load_dword v18, v[18:19], off
	v_add_u32_e32 v4, 0x40000, v2
	v_mov_b32_e32 v5, v3
	v_add_u32_e32 v6, 0x48000, v2
	v_mov_b32_e32 v7, v3
	v_add_u32_e32 v8, 0x50000, v2
	v_mov_b32_e32 v9, v3
	v_add_u32_e32 v10, 0x58000, v2
	v_mov_b32_e32 v11, v3
	v_add_u32_e32 v12, 0x60000, v2
	v_add_u32_e32 v14, 0x68000, v2
	v_add_u32_e32 v16, 0x70000, v2
	v_add_u32_e32 v2, 0x78000, v2
	v_lshl_add_u64 v[4:5], v[4:5], 2, s[8:9]
	v_lshl_add_u64 v[6:7], v[6:7], 2, s[8:9]
	v_lshl_add_u64 v[8:9], v[8:9], 2, s[8:9]
	v_lshl_add_u64 v[10:11], v[10:11], 2, s[8:9]
	v_mov_b32_e32 v13, v3
	v_mov_b32_e32 v15, v3
	v_mov_b32_e32 v17, v3
	v_lshl_add_u64 v[2:3], v[2:3], 2, s[8:9]
	v_lshl_add_u64 v[12:13], v[12:13], 2, s[8:9]
	v_lshl_add_u64 v[14:15], v[14:15], 2, s[8:9]
	v_lshl_add_u64 v[16:17], v[16:17], 2, s[8:9]
	global_load_dword v4, v[4:5], off
	s_nop 0
	global_load_dword v5, v[6:7], off
	s_nop 0
	global_load_dword v6, v[8:9], off
	global_load_dword v7, v[10:11], off
	s_nop 0
	global_load_dword v8, v[12:13], off
	global_load_dword v9, v[14:15], off
	global_load_dword v10, v[16:17], off
	s_nop 0
	global_load_dword v2, v[2:3], off
	v_mov_b32_e32 v3, 0x358637bd
	s_mov_b32 s0, 0xf800000
	s_waitcnt vmcnt(15)
	v_add_f32_e32 v1, 0, v1
	s_waitcnt vmcnt(14)
	v_add_f32_e32 v1, v1, v20
	s_waitcnt vmcnt(13)
	v_add_f32_e32 v1, v1, v21
	s_waitcnt vmcnt(12)
	v_add_f32_e32 v1, v1, v22
	s_waitcnt vmcnt(11)
	v_add_f32_e32 v1, v1, v23
	s_waitcnt vmcnt(10)
	v_add_f32_e32 v1, v1, v24
	s_waitcnt vmcnt(9)
	v_add_f32_e32 v1, v1, v25
	s_waitcnt vmcnt(8)
	v_add_f32_e32 v1, v1, v18
	s_waitcnt vmcnt(7)
	v_add_f32_e32 v1, v1, v4
	s_waitcnt vmcnt(6)
	v_add_f32_e32 v1, v1, v5
	s_waitcnt vmcnt(5)
	v_add_f32_e32 v1, v1, v6
	s_waitcnt vmcnt(4)
	v_add_f32_e32 v1, v1, v7
	s_waitcnt vmcnt(3)
	v_add_f32_e32 v1, v1, v8
	s_waitcnt vmcnt(2)
	v_add_f32_e32 v1, v1, v9
	s_waitcnt vmcnt(1)
	v_add_f32_e32 v1, v1, v10
	s_waitcnt vmcnt(0)
	v_add_f32_e32 v1, v1, v2
	v_fmac_f32_e32 v3, 0x3a800000, v1
	v_mul_f32_e32 v1, 0x4f800000, v3
	v_cmp_gt_f32_e32 vcc, s0, v3
	s_nop 1
	v_cndmask_b32_e32 v1, v3, v1, vcc
	v_sqrt_f32_e32 v2, v1
	v_mov_b32_e32 v3, 0x260
	v_add_u32_e32 v4, -1, v2
	v_add_u32_e32 v5, 1, v2
	v_fma_f32 v6, -v4, v2, v1
	v_fma_f32 v7, -v5, v2, v1
	v_cmp_ge_f32_e64 s[0:1], 0, v6
	s_nop 1
	v_cndmask_b32_e64 v2, v2, v4, s[0:1]
	v_cmp_lt_f32_e64 s[0:1], 0, v7
	s_nop 1
	v_cndmask_b32_e64 v2, v2, v5, s[0:1]
	v_mul_f32_e32 v4, 0x37800000, v2
	v_cndmask_b32_e32 v2, v2, v4, vcc
	v_cmp_class_f32_e32 vcc, v1, v3
	s_nop 1
	v_cndmask_b32_e32 v1, v2, v1, vcc
	v_div_scale_f32 v2, s[0:1], v1, v1, 1.0
	v_rcp_f32_e32 v3, v2
	v_div_scale_f32 v4, vcc, 1.0, v1, 1.0
	v_fma_f32 v5, -v2, v3, 1.0
	v_fmac_f32_e32 v3, v5, v3
	v_mul_f32_e32 v5, v4, v3
	v_fma_f32 v6, -v2, v5, v4
	v_fmac_f32_e32 v5, v6, v3
	v_fma_f32 v2, -v2, v5, v4
	v_div_fmas_f32 v2, v2, v3, v5
	v_div_fixup_f32 v1, v2, v1, 1.0
	ds_write_b32 v0, v1
.LBB0_399:
	s_or_b64 exec, exec, s[10:11]
	s_cmp_lg_u32 s60, s60
	s_cselect_b64 s[0:1], -1, 0
	s_and_b64 s[0:1], s[0:1], s[4:5]
	s_and_saveexec_b64 s[10:11], s[0:1]
	s_cbranch_execz .LBB0_401
	v_lshl_or_b32 v2, s60, 8, v197
	v_mov_b32_e32 v3, 0
	v_add_u32_e32 v18, 0x38000, v2
	v_mov_b32_e32 v19, v3
	v_lshl_add_u64 v[4:5], v[2:3], 2, s[8:9]
	v_add_u32_e32 v6, 0x8000, v2
	v_mov_b32_e32 v7, v3
	v_add_u32_e32 v8, 0x10000, v2
	v_mov_b32_e32 v9, v3
	v_add_u32_e32 v10, 0x18000, v2
	v_mov_b32_e32 v11, v3
	v_add_u32_e32 v12, 0x20000, v2
	v_mov_b32_e32 v13, v3
	v_add_u32_e32 v14, 0x28000, v2
	v_mov_b32_e32 v15, v3
	v_add_u32_e32 v16, 0x30000, v2
	v_mov_b32_e32 v17, v3
	v_lshl_add_u64 v[18:19], v[18:19], 2, s[8:9]
	v_lshl_add_u64 v[6:7], v[6:7], 2, s[8:9]
	v_lshl_add_u64 v[8:9], v[8:9], 2, s[8:9]
	v_lshl_add_u64 v[10:11], v[10:11], 2, s[8:9]
	v_lshl_add_u64 v[12:13], v[12:13], 2, s[8:9]
	v_lshl_add_u64 v[14:15], v[14:15], 2, s[8:9]
	v_lshl_add_u64 v[16:17], v[16:17], 2, s[8:9]
	global_load_dword v1, v[4:5], off
	global_load_dword v20, v[6:7], off
	global_load_dword v21, v[8:9], off
	global_load_dword v22, v[10:11], off
	global_load_dword v23, v[12:13], off
	global_load_dword v24, v[14:15], off
	global_load_dword v25, v[16:17], off
	s_nop 0
	global_load_dword v18, v[18:19], off
	v_add_u32_e32 v4, 0x40000, v2
	v_mov_b32_e32 v5, v3
	v_add_u32_e32 v6, 0x48000, v2
	v_mov_b32_e32 v7, v3
	v_add_u32_e32 v8, 0x50000, v2
	v_mov_b32_e32 v9, v3
	v_add_u32_e32 v10, 0x58000, v2
	v_mov_b32_e32 v11, v3
	v_add_u32_e32 v12, 0x60000, v2
	v_add_u32_e32 v14, 0x68000, v2
	v_add_u32_e32 v16, 0x70000, v2
	v_add_u32_e32 v2, 0x78000, v2
	v_lshl_add_u64 v[4:5], v[4:5], 2, s[8:9]
	v_lshl_add_u64 v[6:7], v[6:7], 2, s[8:9]
	v_lshl_add_u64 v[8:9], v[8:9], 2, s[8:9]
	v_lshl_add_u64 v[10:11], v[10:11], 2, s[8:9]
	v_mov_b32_e32 v13, v3
	v_mov_b32_e32 v15, v3
	v_mov_b32_e32 v17, v3
	v_lshl_add_u64 v[2:3], v[2:3], 2, s[8:9]
	v_lshl_add_u64 v[12:13], v[12:13], 2, s[8:9]
	v_lshl_add_u64 v[14:15], v[14:15], 2, s[8:9]
	v_lshl_add_u64 v[16:17], v[16:17], 2, s[8:9]
	global_load_dword v4, v[4:5], off
	s_nop 0
	global_load_dword v5, v[6:7], off
	s_nop 0
	global_load_dword v6, v[8:9], off
	global_load_dword v7, v[10:11], off
	s_nop 0
	global_load_dword v8, v[12:13], off
	global_load_dword v9, v[14:15], off
	global_load_dword v10, v[16:17], off
	s_nop 0
	global_load_dword v2, v[2:3], off
	v_mov_b32_e32 v3, 0x358637bd
	s_mov_b32 s0, 0xf800000
	s_waitcnt vmcnt(15)
	v_add_f32_e32 v1, 0, v1
	s_waitcnt vmcnt(14)
	v_add_f32_e32 v1, v1, v20
	s_waitcnt vmcnt(13)
	v_add_f32_e32 v1, v1, v21
	s_waitcnt vmcnt(12)
	v_add_f32_e32 v1, v1, v22
	s_waitcnt vmcnt(11)
	v_add_f32_e32 v1, v1, v23
	s_waitcnt vmcnt(10)
	v_add_f32_e32 v1, v1, v24
	s_waitcnt vmcnt(9)
	v_add_f32_e32 v1, v1, v25
	s_waitcnt vmcnt(8)
	v_add_f32_e32 v1, v1, v18
	s_waitcnt vmcnt(7)
	v_add_f32_e32 v1, v1, v4
	s_waitcnt vmcnt(6)
	v_add_f32_e32 v1, v1, v5
	s_waitcnt vmcnt(5)
	v_add_f32_e32 v1, v1, v6
	s_waitcnt vmcnt(4)
	v_add_f32_e32 v1, v1, v7
	s_waitcnt vmcnt(3)
	v_add_f32_e32 v1, v1, v8
	s_waitcnt vmcnt(2)
	v_add_f32_e32 v1, v1, v9
	s_waitcnt vmcnt(1)
	v_add_f32_e32 v1, v1, v10
	s_waitcnt vmcnt(0)
	v_add_f32_e32 v1, v1, v2
	v_fmac_f32_e32 v3, 0x3a800000, v1
	v_mul_f32_e32 v1, 0x4f800000, v3
	v_cmp_gt_f32_e32 vcc, s0, v3
	s_nop 1
	v_cndmask_b32_e32 v1, v3, v1, vcc
	v_sqrt_f32_e32 v2, v1
	v_mov_b32_e32 v3, 0x260
	v_add_u32_e32 v4, -1, v2
	v_add_u32_e32 v5, 1, v2
	v_fma_f32 v6, -v4, v2, v1
	v_fma_f32 v7, -v5, v2, v1
	v_cmp_ge_f32_e64 s[0:1], 0, v6
	s_nop 1
	v_cndmask_b32_e64 v2, v2, v4, s[0:1]
	v_cmp_lt_f32_e64 s[0:1], 0, v7
	s_nop 1
	v_cndmask_b32_e64 v2, v2, v5, s[0:1]
	v_mul_f32_e32 v4, 0x37800000, v2
	v_cndmask_b32_e32 v2, v2, v4, vcc
	v_cmp_class_f32_e32 vcc, v1, v3
	s_nop 1
	v_cndmask_b32_e32 v1, v2, v1, vcc
	v_div_scale_f32 v2, s[0:1], v1, v1, 1.0
	v_rcp_f32_e32 v3, v2
	v_div_scale_f32 v4, vcc, 1.0, v1, 1.0
	v_fma_f32 v5, -v2, v3, 1.0
	v_fmac_f32_e32 v3, v5, v3
	v_mul_f32_e32 v5, v4, v3
	v_fma_f32 v6, -v2, v5, v4
	v_fmac_f32_e32 v5, v6, v3
	v_fma_f32 v2, -v2, v5, v4
	v_div_fmas_f32 v2, v2, v3, v5
	v_div_fixup_f32 v1, v2, v1, 1.0
	ds_write_b32 v0, v1 offset:1024

.LBB0_782:
	s_cmp_lt_i32 s30, 9
	s_cselect_b64 s[0:1], -1, 0
	s_and_b64 s[6:7], s[0:1], s[4:5]
	s_andn2_b64 vcc, exec, s[6:7]
	s_cbranch_vccnz .LBB0_817
	s_ashr_i32 s3, s2, 31
	s_ashr_i32 s33, s22, 31
	s_mov_b32 s46, s22
	s_mov_b32 s47, -1
	s_mov_b32 s4, 16
	s_waitcnt lgkmcnt(0)
	v_mov_b64_e32 v[0:1], 0xaff
	s_mov_b64 s[0:1], s[2:3]
	s_mov_b32 s49, -1
	s_mov_b32 s48, -1
	s_mov_b32 s12, -1
	s_and_b32 s5, s2, 7
	s_lshl_b32 s5, s5, 4
	s_bfe_u32 s8, s2, 0x30003
	s_add_i32 s47, s5, s8
	s_add_i32 s49, s47, 8
.LBB0_793:
	s_add_u32 s8, s28, 0x5c00000
	s_movk_i32 s0, 0x100
	s_addc_u32 s9, s29, 0
	v_cmp_gt_u32_e64 s[4:5], s0, v197
	s_add_i32 s0, 0, 0x20000
	s_cmp_gt_i32 s47, -1
	v_lshl_add_u32 v0, v197, 2, s0
	s_cselect_b64 s[0:1], -1, 0
	s_and_b64 s[0:1], s[0:1], exec
	s_waitcnt vmcnt(0)
	s_barrier
	s_and_saveexec_b64 s[10:11], s[0:1]
	s_cbranch_execz .LBB0_795
	v_mov_b32_e32 v30, s47
	v_mov_b32_e32 v31, s49
	v_cmp_lt_u32_e32 vcc, 0xff, v197
	v_and_b32_e32 v2, 0xff, v197
	s_nop 0
	v_cndmask_b32_e32 v30, v30, v31, vcc
	v_lshl_or_b32 v2, v30, 8, v2
	v_mov_b32_e32 v3, 0
	v_lshl_add_u64 v[4:5], v[2:3], 2, s[8:9]
	v_add_u32_e32 v6, 0x8000, v2
	v_mov_b32_e32 v7, v3
	v_add_u32_e32 v8, 0x10000, v2
	v_mov_b32_e32 v9, v3
	v_add_u32_e32 v10, 0x18000, v2
	v_mov_b32_e32 v11, v3
	v_add_u32_e32 v12, 0x20000, v2
	v_mov_b32_e32 v13, v3
	v_add_u32_e32 v14, 0x28000, v2
	v_mov_b32_e32 v15, v3
	v_add_u32_e32 v16, 0x30000, v2
	v_mov_b32_e32 v17, v3
	v_add_u32_e32 v18, 0x38000, v2
	v_mov_b32_e32 v19, v3
	v_lshl_add_u64 v[6:7], v[6:7], 2, s[8:9]
	v_lshl_add_u64 v[8:9], v[8:9], 2, s[8:9]
	v_lshl_add_u64 v[10:11], v[10:11], 2, s[8:9]
	v_lshl_add_u64 v[12:13], v[12:13], 2, s[8:9]
	v_lshl_add_u64 v[14:15], v[14:15], 2, s[8:9]
	v_lshl_add_u64 v[16:17], v[16:17], 2, s[8:9]
	v_lshl_add_u64 v[18:19], v[18:19], 2, s[8:9]
	global_load_dword v1, v[4:5], off
	global_load_dword v20, v[6:7], off
	global_load_dword v21, v[8:9], off
	global_load_dword v22, v[10:11], off
	global_load_dword v23, v[12:13], off
	global_load_dword v24, v[14:15], off
	global_load_dword v25, v[16:17], off
	global_load_dword v26, v[18:19], off
	v_add_u32_e32 v4, 0x40000, v2
	v_mov_b32_e32 v5, v3
	v_lshl_add_u64 v[4:5], v[4:5], 2, s[8:9]
	v_add_u32_e32 v6, 0x48000, v2
	v_mov_b32_e32 v7, v3
	v_add_u32_e32 v8, 0x50000, v2
	v_mov_b32_e32 v9, v3
	v_add_u32_e32 v10, 0x58000, v2
	v_mov_b32_e32 v11, v3
	v_add_u32_e32 v12, 0x60000, v2
	v_mov_b32_e32 v13, v3
	v_add_u32_e32 v14, 0x68000, v2
	v_mov_b32_e32 v15, v3
	v_add_u32_e32 v16, 0x70000, v2
	v_mov_b32_e32 v17, v3
	v_add_u32_e32 v2, 0x78000, v2
	v_lshl_add_u64 v[6:7], v[6:7], 2, s[8:9]
	v_lshl_add_u64 v[8:9], v[8:9], 2, s[8:9]
	v_lshl_add_u64 v[10:11], v[10:11], 2, s[8:9]
	v_lshl_add_u64 v[12:13], v[12:13], 2, s[8:9]
	v_lshl_add_u64 v[14:15], v[14:15], 2, s[8:9]
	v_lshl_add_u64 v[16:17], v[16:17], 2, s[8:9]
	v_lshl_add_u64 v[2:3], v[2:3], 2, s[8:9]
	global_load_dword v18, v[4:5], off
	global_load_dword v19, v[6:7], off
	global_load_dword v27, v[8:9], off
	global_load_dword v28, v[10:11], off
	global_load_dword v29, v[12:13], off
	global_load_dword v30, v[14:15], off
	global_load_dword v31, v[16:17], off
	global_load_dword v32, v[2:3], off
	v_mov_b32_e32 v2, 0x358637bd
	s_mov_b32 s0, 0xf800000
	v_mov_b32_e32 v3, 0x260
	s_waitcnt vmcnt(15)
	v_add_f32_e32 v1, 0, v1
	s_waitcnt vmcnt(14)
	v_add_f32_e32 v1, v1, v20
	s_waitcnt vmcnt(13)
	v_add_f32_e32 v1, v1, v21
	s_waitcnt vmcnt(12)
	v_add_f32_e32 v1, v1, v22
	s_waitcnt vmcnt(11)
	v_add_f32_e32 v1, v1, v23
	s_waitcnt vmcnt(10)
	v_add_f32_e32 v1, v1, v24
	s_waitcnt vmcnt(9)
	v_add_f32_e32 v1, v1, v25
	s_waitcnt vmcnt(8)
	v_add_f32_e32 v1, v1, v26
	s_waitcnt vmcnt(7)
	v_add_f32_e32 v1, v1, v18
	s_waitcnt vmcnt(6)
	v_add_f32_e32 v1, v1, v19
	s_waitcnt vmcnt(5)
	v_add_f32_e32 v1, v1, v27
	s_waitcnt vmcnt(4)
	v_add_f32_e32 v1, v1, v28
	s_waitcnt vmcnt(3)
	v_add_f32_e32 v1, v1, v29
	s_waitcnt vmcnt(2)
	v_add_f32_e32 v1, v1, v30
	s_waitcnt vmcnt(1)
	v_add_f32_e32 v1, v1, v31
	s_waitcnt vmcnt(0)
	v_add_f32_e32 v1, v1, v32
	v_fmac_f32_e32 v2, 0x3a800000, v1
	v_mul_f32_e32 v1, 0x4f800000, v2
	v_cmp_gt_f32_e32 vcc, s0, v2
	s_nop 1
	v_cndmask_b32_e32 v1, v2, v1, vcc
	v_sqrt_f32_e32 v2, v1
	s_nop 0
	v_add_u32_e32 v4, -1, v2
	v_add_u32_e32 v5, 1, v2
	v_fma_f32 v6, -v4, v2, v1
	v_fma_f32 v7, -v5, v2, v1
	v_cmp_ge_f32_e64 s[0:1], 0, v6
	s_nop 1
	v_cndmask_b32_e64 v2, v2, v4, s[0:1]
	v_cmp_lt_f32_e64 s[0:1], 0, v7
	s_nop 1
	v_cndmask_b32_e64 v2, v2, v5, s[0:1]
	v_mul_f32_e32 v4, 0x37800000, v2
	v_cndmask_b32_e32 v2, v2, v4, vcc
	v_cmp_class_f32_e32 vcc, v1, v3
	s_nop 1
	v_cndmask_b32_e32 v1, v2, v1, vcc
	v_div_scale_f32 v2, s[0:1], v1, v1, 1.0
	v_rcp_f32_e32 v3, v2
	v_div_scale_f32 v4, vcc, 1.0, v1, 1.0
	v_fma_f32 v5, -v2, v3, 1.0
	v_fmac_f32_e32 v3, v5, v3
	v_mul_f32_e32 v5, v4, v3
	v_fma_f32 v6, -v2, v5, v4
	v_fmac_f32_e32 v5, v6, v3
	v_fma_f32 v2, -v2, v5, v4
	v_div_fmas_f32 v2, v2, v3, v5
	v_div_fixup_f32 v1, v2, v1, 1.0
	ds_write_b32 v0, v1
.LBB0_795:
	s_or_b64 exec, exec, s[10:11]
	s_cmp_lg_u32 s49, s49
	s_cselect_b64 s[0:1], -1, 0
	s_and_b64 s[0:1], s[0:1], s[4:5]
	s_and_saveexec_b64 s[10:11], s[0:1]
	s_cbranch_execz .LBB0_797
	v_lshl_or_b32 v2, s49, 8, v197
	v_mov_b32_e32 v3, 0
	v_lshl_add_u64 v[4:5], v[2:3], 2, s[8:9]
	v_add_u32_e32 v6, 0x8000, v2
	v_mov_b32_e32 v7, v3
	v_add_u32_e32 v8, 0x10000, v2
	v_mov_b32_e32 v9, v3
	v_add_u32_e32 v10, 0x18000, v2
	v_mov_b32_e32 v11, v3
	v_add_u32_e32 v12, 0x20000, v2
	v_mov_b32_e32 v13, v3
	v_add_u32_e32 v14, 0x28000, v2
	v_mov_b32_e32 v15, v3
	v_add_u32_e32 v16, 0x30000, v2
	v_mov_b32_e32 v17, v3
	v_add_u32_e32 v18, 0x38000, v2
	v_mov_b32_e32 v19, v3
	v_lshl_add_u64 v[6:7], v[6:7], 2, s[8:9]
	v_lshl_add_u64 v[8:9], v[8:9], 2, s[8:9]
	v_lshl_add_u64 v[10:11], v[10:11], 2, s[8:9]
	v_lshl_add_u64 v[12:13], v[12:13], 2, s[8:9]
	v_lshl_add_u64 v[14:15], v[14:15], 2, s[8:9]
	v_lshl_add_u64 v[16:17], v[16:17], 2, s[8:9]
	v_lshl_add_u64 v[18:19], v[18:19], 2, s[8:9]
	global_load_dword v1, v[4:5], off
	global_load_dword v20, v[6:7], off
	global_load_dword v21, v[8:9], off
	global_load_dword v22, v[10:11], off
	global_load_dword v23, v[12:13], off
	global_load_dword v24, v[14:15], off
	global_load_dword v25, v[16:17], off
	global_load_dword v26, v[18:19], off
	v_add_u32_e32 v4, 0x40000, v2
	v_mov_b32_e32 v5, v3
	v_lshl_add_u64 v[4:5], v[4:5], 2, s[8:9]
	v_add_u32_e32 v6, 0x48000, v2
	v_mov_b32_e32 v7, v3
	v_add_u32_e32 v8, 0x50000, v2
	v_mov_b32_e32 v9, v3
	v_add_u32_e32 v10, 0x58000, v2
	v_mov_b32_e32 v11, v3
	v_add_u32_e32 v12, 0x60000, v2
	v_mov_b32_e32 v13, v3
	v_add_u32_e32 v14, 0x68000, v2
	v_mov_b32_e32 v15, v3
	v_add_u32_e32 v16, 0x70000, v2
	v_mov_b32_e32 v17, v3
	v_add_u32_e32 v2, 0x78000, v2
	v_lshl_add_u64 v[6:7], v[6:7], 2, s[8:9]
	v_lshl_add_u64 v[8:9], v[8:9], 2, s[8:9]
	v_lshl_add_u64 v[10:11], v[10:11], 2, s[8:9]
	v_lshl_add_u64 v[12:13], v[12:13], 2, s[8:9]
	v_lshl_add_u64 v[14:15], v[14:15], 2, s[8:9]
	v_lshl_add_u64 v[16:17], v[16:17], 2, s[8:9]
	v_lshl_add_u64 v[2:3], v[2:3], 2, s[8:9]
	global_load_dword v18, v[4:5], off
	global_load_dword v19, v[6:7], off
	global_load_dword v27, v[8:9], off
	global_load_dword v28, v[10:11], off
	global_load_dword v29, v[12:13], off
	global_load_dword v30, v[14:15], off
	global_load_dword v31, v[16:17], off
	global_load_dword v32, v[2:3], off
	v_mov_b32_e32 v2, 0x358637bd
	s_mov_b32 s0, 0xf800000
	v_mov_b32_e32 v3, 0x260
	s_waitcnt vmcnt(15)
	v_add_f32_e32 v1, 0, v1
	s_waitcnt vmcnt(14)
	v_add_f32_e32 v1, v1, v20
	s_waitcnt vmcnt(13)
	v_add_f32_e32 v1, v1, v21
	s_waitcnt vmcnt(12)
	v_add_f32_e32 v1, v1, v22
	s_waitcnt vmcnt(11)
	v_add_f32_e32 v1, v1, v23
	s_waitcnt vmcnt(10)
	v_add_f32_e32 v1, v1, v24
	s_waitcnt vmcnt(9)
	v_add_f32_e32 v1, v1, v25
	s_waitcnt vmcnt(8)
	v_add_f32_e32 v1, v1, v26
	s_waitcnt vmcnt(7)
	v_add_f32_e32 v1, v1, v18
	s_waitcnt vmcnt(6)
	v_add_f32_e32 v1, v1, v19
	s_waitcnt vmcnt(5)
	v_add_f32_e32 v1, v1, v27
	s_waitcnt vmcnt(4)
	v_add_f32_e32 v1, v1, v28
	s_waitcnt vmcnt(3)
	v_add_f32_e32 v1, v1, v29
	s_waitcnt vmcnt(2)
	v_add_f32_e32 v1, v1, v30
	s_waitcnt vmcnt(1)
	v_add_f32_e32 v1, v1, v31
	s_waitcnt vmcnt(0)
	v_add_f32_e32 v1, v1, v32
	v_fmac_f32_e32 v2, 0x3a800000, v1
	v_mul_f32_e32 v1, 0x4f800000, v2
	v_cmp_gt_f32_e32 vcc, s0, v2
	s_nop 1
	v_cndmask_b32_e32 v1, v2, v1, vcc
	v_sqrt_f32_e32 v2, v1
	s_nop 0
	v_add_u32_e32 v4, -1, v2
	v_add_u32_e32 v5, 1, v2
	v_fma_f32 v6, -v4, v2, v1
	v_fma_f32 v7, -v5, v2, v1
	v_cmp_ge_f32_e64 s[0:1], 0, v6
	s_nop 1
	v_cndmask_b32_e64 v2, v2, v4, s[0:1]
	v_cmp_lt_f32_e64 s[0:1], 0, v7
	s_nop 1
	v_cndmask_b32_e64 v2, v2, v5, s[0:1]
	v_mul_f32_e32 v4, 0x37800000, v2
	v_cndmask_b32_e32 v2, v2, v4, vcc
	v_cmp_class_f32_e32 vcc, v1, v3
	s_nop 1
	v_cndmask_b32_e32 v1, v2, v1, vcc
	v_div_scale_f32 v2, s[0:1], v1, v1, 1.0
	v_rcp_f32_e32 v3, v2
	v_div_scale_f32 v4, vcc, 1.0, v1, 1.0
	v_fma_f32 v5, -v2, v3, 1.0
	v_fmac_f32_e32 v3, v5, v3
	v_mul_f32_e32 v5, v4, v3
	v_fma_f32 v6, -v2, v5, v4
	v_fmac_f32_e32 v5, v6, v3
	v_fma_f32 v2, -v2, v5, v4
	v_div_fmas_f32 v2, v2, v3, v5
	v_div_fixup_f32 v1, v2, v1, 1.0
	ds_write_b32 v0, v1 offset:1024

.LBB0_972:
	s_cmp_lt_i32 s30, 11
	s_cselect_b64 s[4:5], -1, 0
	s_and_b64 s[6:7], s[4:5], s[0:1]
	s_andn2_b64 vcc, exec, s[6:7]
	s_cbranch_vccnz .LBB0_1007
	s_ashr_i32 s3, s2, 31
	s_ashr_i32 s33, s22, 31
	s_mov_b32 s46, s22
	s_mov_b32 s47, -1
	s_mov_b32 s4, 16
	s_waitcnt lgkmcnt(0)
	v_mov_b64_e32 v[0:1], 0xaff
	s_mov_b64 s[0:1], s[2:3]
	s_mov_b32 s49, -1
	s_mov_b32 s48, -1
	s_mov_b32 s12, -1
	s_and_b32 s5, s2, 7
	s_lshl_b32 s5, s5, 4
	s_bfe_u32 s8, s2, 0x30003
	s_add_i32 s47, s5, s8
	s_add_i32 s49, s47, 8
.LBB0_983:
	s_add_u32 s8, s28, 0x5e00000
	s_movk_i32 s0, 0x100
	s_addc_u32 s9, s29, 0
	v_cmp_gt_u32_e64 s[4:5], s0, v197
	s_add_i32 s0, 0, 0x20000
	s_cmp_gt_i32 s47, -1
	v_lshl_add_u32 v0, v197, 2, s0
	s_cselect_b64 s[0:1], -1, 0
	s_and_b64 s[0:1], s[0:1], exec
	s_waitcnt vmcnt(0)
	s_barrier
	s_and_saveexec_b64 s[10:11], s[0:1]
	s_cbranch_execz .LBB0_985
	v_mov_b32_e32 v30, s47
	v_mov_b32_e32 v31, s49
	v_cmp_lt_u32_e32 vcc, 0xff, v197
	v_and_b32_e32 v2, 0xff, v197
	s_nop 0
	v_cndmask_b32_e32 v30, v30, v31, vcc
	v_lshl_or_b32 v2, v30, 8, v2
	v_mov_b32_e32 v3, 0
	v_lshl_add_u64 v[4:5], v[2:3], 2, s[8:9]
	v_add_u32_e32 v6, 0x8000, v2
	v_mov_b32_e32 v7, v3
	v_add_u32_e32 v8, 0x10000, v2
	v_mov_b32_e32 v9, v3
	v_add_u32_e32 v10, 0x18000, v2
	v_mov_b32_e32 v11, v3
	v_add_u32_e32 v12, 0x20000, v2
	v_mov_b32_e32 v13, v3
	v_add_u32_e32 v14, 0x28000, v2
	v_mov_b32_e32 v15, v3
	v_add_u32_e32 v16, 0x30000, v2
	v_mov_b32_e32 v17, v3
	v_add_u32_e32 v18, 0x38000, v2
	v_mov_b32_e32 v19, v3
	v_lshl_add_u64 v[6:7], v[6:7], 2, s[8:9]
	v_lshl_add_u64 v[8:9], v[8:9], 2, s[8:9]
	v_lshl_add_u64 v[10:11], v[10:11], 2, s[8:9]
	v_lshl_add_u64 v[12:13], v[12:13], 2, s[8:9]
	v_lshl_add_u64 v[14:15], v[14:15], 2, s[8:9]
	v_lshl_add_u64 v[16:17], v[16:17], 2, s[8:9]
	v_lshl_add_u64 v[18:19], v[18:19], 2, s[8:9]
	global_load_dword v1, v[4:5], off
	global_load_dword v20, v[6:7], off
	global_load_dword v21, v[8:9], off
	global_load_dword v22, v[10:11], off
	global_load_dword v23, v[12:13], off
	global_load_dword v24, v[14:15], off
	global_load_dword v25, v[16:17], off
	global_load_dword v26, v[18:19], off
	v_add_u32_e32 v4, 0x40000, v2
	v_mov_b32_e32 v5, v3
	v_lshl_add_u64 v[4:5], v[4:5], 2, s[8:9]
	v_add_u32_e32 v6, 0x48000, v2
	v_mov_b32_e32 v7, v3
	v_add_u32_e32 v8, 0x50000, v2
	v_mov_b32_e32 v9, v3
	v_add_u32_e32 v10, 0x58000, v2
	v_mov_b32_e32 v11, v3
	v_add_u32_e32 v12, 0x60000, v2
	v_mov_b32_e32 v13, v3
	v_add_u32_e32 v14, 0x68000, v2
	v_mov_b32_e32 v15, v3
	v_add_u32_e32 v16, 0x70000, v2
	v_mov_b32_e32 v17, v3
	v_add_u32_e32 v2, 0x78000, v2
	v_lshl_add_u64 v[6:7], v[6:7], 2, s[8:9]
	v_lshl_add_u64 v[8:9], v[8:9], 2, s[8:9]
	v_lshl_add_u64 v[10:11], v[10:11], 2, s[8:9]
	v_lshl_add_u64 v[12:13], v[12:13], 2, s[8:9]
	v_lshl_add_u64 v[14:15], v[14:15], 2, s[8:9]
	v_lshl_add_u64 v[16:17], v[16:17], 2, s[8:9]
	v_lshl_add_u64 v[2:3], v[2:3], 2, s[8:9]
	global_load_dword v18, v[4:5], off
	global_load_dword v19, v[6:7], off
	global_load_dword v27, v[8:9], off
	global_load_dword v28, v[10:11], off
	global_load_dword v29, v[12:13], off
	global_load_dword v30, v[14:15], off
	global_load_dword v31, v[16:17], off
	global_load_dword v32, v[2:3], off
	v_mov_b32_e32 v2, 0x358637bd
	s_mov_b32 s0, 0xf800000
	v_mov_b32_e32 v3, 0x260
	s_waitcnt vmcnt(15)
	v_add_f32_e32 v1, 0, v1
	s_waitcnt vmcnt(14)
	v_add_f32_e32 v1, v1, v20
	s_waitcnt vmcnt(13)
	v_add_f32_e32 v1, v1, v21
	s_waitcnt vmcnt(12)
	v_add_f32_e32 v1, v1, v22
	s_waitcnt vmcnt(11)
	v_add_f32_e32 v1, v1, v23
	s_waitcnt vmcnt(10)
	v_add_f32_e32 v1, v1, v24
	s_waitcnt vmcnt(9)
	v_add_f32_e32 v1, v1, v25
	s_waitcnt vmcnt(8)
	v_add_f32_e32 v1, v1, v26
	s_waitcnt vmcnt(7)
	v_add_f32_e32 v1, v1, v18
	s_waitcnt vmcnt(6)
	v_add_f32_e32 v1, v1, v19
	s_waitcnt vmcnt(5)
	v_add_f32_e32 v1, v1, v27
	s_waitcnt vmcnt(4)
	v_add_f32_e32 v1, v1, v28
	s_waitcnt vmcnt(3)
	v_add_f32_e32 v1, v1, v29
	s_waitcnt vmcnt(2)
	v_add_f32_e32 v1, v1, v30
	s_waitcnt vmcnt(1)
	v_add_f32_e32 v1, v1, v31
	s_waitcnt vmcnt(0)
	v_add_f32_e32 v1, v1, v32
	v_fmac_f32_e32 v2, 0x3a800000, v1
	v_mul_f32_e32 v1, 0x4f800000, v2
	v_cmp_gt_f32_e32 vcc, s0, v2
	s_nop 1
	v_cndmask_b32_e32 v1, v2, v1, vcc
	v_sqrt_f32_e32 v2, v1
	s_nop 0
	v_add_u32_e32 v4, -1, v2
	v_add_u32_e32 v5, 1, v2
	v_fma_f32 v6, -v4, v2, v1
	v_fma_f32 v7, -v5, v2, v1
	v_cmp_ge_f32_e64 s[0:1], 0, v6
	s_nop 1
	v_cndmask_b32_e64 v2, v2, v4, s[0:1]
	v_cmp_lt_f32_e64 s[0:1], 0, v7
	s_nop 1
	v_cndmask_b32_e64 v2, v2, v5, s[0:1]
	v_mul_f32_e32 v4, 0x37800000, v2
	v_cndmask_b32_e32 v2, v2, v4, vcc
	v_cmp_class_f32_e32 vcc, v1, v3
	s_nop 1
	v_cndmask_b32_e32 v1, v2, v1, vcc
	v_div_scale_f32 v2, s[0:1], v1, v1, 1.0
	v_rcp_f32_e32 v3, v2
	v_div_scale_f32 v4, vcc, 1.0, v1, 1.0
	v_fma_f32 v5, -v2, v3, 1.0
	v_fmac_f32_e32 v3, v5, v3
	v_mul_f32_e32 v5, v4, v3
	v_fma_f32 v6, -v2, v5, v4
	v_fmac_f32_e32 v5, v6, v3
	v_fma_f32 v2, -v2, v5, v4
	v_div_fmas_f32 v2, v2, v3, v5
	v_div_fixup_f32 v1, v2, v1, 1.0
	ds_write_b32 v0, v1

.LBB0_1712:
	s_cmp_lt_i32 s30, 17
	s_cselect_b64 s[0:1], -1, 0
	s_and_b64 s[6:7], s[0:1], s[4:5]
	s_andn2_b64 vcc, exec, s[6:7]
	s_cbranch_vccnz .LBB0_1747
	s_ashr_i32 s3, s2, 31
	s_ashr_i32 s33, s22, 31
	s_mov_b32 s44, s22
	s_mov_b32 s12, -1
	s_mov_b32 s4, 16
	s_waitcnt lgkmcnt(0)
	v_mov_b64_e32 v[0:1], 0xaff
	s_mov_b64 s[0:1], s[2:3]
	s_mov_b32 s45, -1
	s_mov_b32 s46, -1
	s_mov_b32 s47, -1
	s_and_b32 s5, s2, 7
	s_lshl_b32 s5, s5, 4
	s_bfe_u32 s8, s2, 0x30003
	s_add_i32 s47, s5, s8
	s_add_i32 s46, s47, 8
.LBB0_1723:
	s_add_u32 s8, s28, 0x6200000
	s_movk_i32 s0, 0x100
	s_addc_u32 s9, s29, 0
	v_cmp_gt_u32_e64 s[4:5], s0, v197
	s_add_i32 s0, 0, 0x20000
	s_cmp_gt_i32 s47, -1
	v_lshl_add_u32 v0, v197, 2, s0
	s_cselect_b64 s[0:1], -1, 0
	s_and_b64 s[0:1], s[0:1], exec
	s_waitcnt vmcnt(0)
	s_barrier
	s_and_saveexec_b64 s[10:11], s[0:1]
	s_cbranch_execz .LBB0_1725
	v_mov_b32_e32 v30, s47
	v_mov_b32_e32 v31, s46
	v_cmp_lt_u32_e32 vcc, 0xff, v197
	v_and_b32_e32 v2, 0xff, v197
	s_nop 0
	v_cndmask_b32_e32 v30, v30, v31, vcc
	v_lshl_or_b32 v2, v30, 8, v2
	v_mov_b32_e32 v3, 0
	v_lshl_add_u64 v[4:5], v[2:3], 2, s[8:9]
	v_add_u32_e32 v6, 0x8000, v2
	v_mov_b32_e32 v7, v3
	v_add_u32_e32 v8, 0x10000, v2
	v_mov_b32_e32 v9, v3
	v_add_u32_e32 v10, 0x18000, v2
	v_mov_b32_e32 v11, v3
	v_add_u32_e32 v12, 0x20000, v2
	v_mov_b32_e32 v13, v3
	v_add_u32_e32 v14, 0x28000, v2
	v_mov_b32_e32 v15, v3
	v_add_u32_e32 v16, 0x30000, v2
	v_mov_b32_e32 v17, v3
	v_add_u32_e32 v18, 0x38000, v2
	v_mov_b32_e32 v19, v3
	v_lshl_add_u64 v[6:7], v[6:7], 2, s[8:9]
	v_lshl_add_u64 v[8:9], v[8:9], 2, s[8:9]
	v_lshl_add_u64 v[10:11], v[10:11], 2, s[8:9]
	v_lshl_add_u64 v[12:13], v[12:13], 2, s[8:9]
	v_lshl_add_u64 v[14:15], v[14:15], 2, s[8:9]
	v_lshl_add_u64 v[16:17], v[16:17], 2, s[8:9]
	v_lshl_add_u64 v[18:19], v[18:19], 2, s[8:9]
	global_load_dword v1, v[4:5], off
	global_load_dword v20, v[6:7], off
	global_load_dword v21, v[8:9], off
	global_load_dword v22, v[10:11], off
	global_load_dword v23, v[12:13], off
	global_load_dword v24, v[14:15], off
	global_load_dword v25, v[16:17], off
	global_load_dword v26, v[18:19], off
	v_add_u32_e32 v4, 0x40000, v2
	v_mov_b32_e32 v5, v3
	v_lshl_add_u64 v[4:5], v[4:5], 2, s[8:9]
	v_add_u32_e32 v6, 0x48000, v2
	v_mov_b32_e32 v7, v3
	v_add_u32_e32 v8, 0x50000, v2
	v_mov_b32_e32 v9, v3
	v_add_u32_e32 v10, 0x58000, v2
	v_mov_b32_e32 v11, v3
	v_add_u32_e32 v12, 0x60000, v2
	v_mov_b32_e32 v13, v3
	v_add_u32_e32 v14, 0x68000, v2
	v_mov_b32_e32 v15, v3
	v_add_u32_e32 v16, 0x70000, v2
	v_mov_b32_e32 v17, v3
	v_add_u32_e32 v2, 0x78000, v2
	v_lshl_add_u64 v[6:7], v[6:7], 2, s[8:9]
	v_lshl_add_u64 v[8:9], v[8:9], 2, s[8:9]
	v_lshl_add_u64 v[10:11], v[10:11], 2, s[8:9]
	v_lshl_add_u64 v[12:13], v[12:13], 2, s[8:9]
	v_lshl_add_u64 v[14:15], v[14:15], 2, s[8:9]
	v_lshl_add_u64 v[16:17], v[16:17], 2, s[8:9]
	v_lshl_add_u64 v[2:3], v[2:3], 2, s[8:9]
	global_load_dword v18, v[4:5], off
	global_load_dword v19, v[6:7], off
	global_load_dword v27, v[8:9], off
	global_load_dword v28, v[10:11], off
	global_load_dword v29, v[12:13], off
	global_load_dword v30, v[14:15], off
	global_load_dword v31, v[16:17], off
	global_load_dword v32, v[2:3], off
	v_mov_b32_e32 v2, 0x358637bd
	s_mov_b32 s0, 0xf800000
	v_mov_b32_e32 v3, 0x260
	s_waitcnt vmcnt(15)
	v_add_f32_e32 v1, 0, v1
	s_waitcnt vmcnt(14)
	v_add_f32_e32 v1, v1, v20
	s_waitcnt vmcnt(13)
	v_add_f32_e32 v1, v1, v21
	s_waitcnt vmcnt(12)
	v_add_f32_e32 v1, v1, v22
	s_waitcnt vmcnt(11)
	v_add_f32_e32 v1, v1, v23
	s_waitcnt vmcnt(10)
	v_add_f32_e32 v1, v1, v24
	s_waitcnt vmcnt(9)
	v_add_f32_e32 v1, v1, v25
	s_waitcnt vmcnt(8)
	v_add_f32_e32 v1, v1, v26
	s_waitcnt vmcnt(7)
	v_add_f32_e32 v1, v1, v18
	s_waitcnt vmcnt(6)
	v_add_f32_e32 v1, v1, v19
	s_waitcnt vmcnt(5)
	v_add_f32_e32 v1, v1, v27
	s_waitcnt vmcnt(4)
	v_add_f32_e32 v1, v1, v28
	s_waitcnt vmcnt(3)
	v_add_f32_e32 v1, v1, v29
	s_waitcnt vmcnt(2)
	v_add_f32_e32 v1, v1, v30
	s_waitcnt vmcnt(1)
	v_add_f32_e32 v1, v1, v31
	s_waitcnt vmcnt(0)
	v_add_f32_e32 v1, v1, v32
	v_fmac_f32_e32 v2, 0x3a800000, v1
	v_mul_f32_e32 v1, 0x4f800000, v2
	v_cmp_gt_f32_e32 vcc, s0, v2
	s_nop 1
	v_cndmask_b32_e32 v1, v2, v1, vcc
	v_sqrt_f32_e32 v2, v1
	s_nop 0
	v_add_u32_e32 v4, -1, v2
	v_add_u32_e32 v5, 1, v2
	v_fma_f32 v6, -v4, v2, v1
	v_fma_f32 v7, -v5, v2, v1
	v_cmp_ge_f32_e64 s[0:1], 0, v6
	s_nop 1
	v_cndmask_b32_e64 v2, v2, v4, s[0:1]
	v_cmp_lt_f32_e64 s[0:1], 0, v7
	s_nop 1
	v_cndmask_b32_e64 v2, v2, v5, s[0:1]
	v_mul_f32_e32 v4, 0x37800000, v2
	v_cndmask_b32_e32 v2, v2, v4, vcc
	v_cmp_class_f32_e32 vcc, v1, v3
	s_nop 1
	v_cndmask_b32_e32 v1, v2, v1, vcc
	v_div_scale_f32 v2, s[0:1], v1, v1, 1.0
	v_rcp_f32_e32 v3, v2
	v_div_scale_f32 v4, vcc, 1.0, v1, 1.0
	v_fma_f32 v5, -v2, v3, 1.0
	v_fmac_f32_e32 v3, v5, v3
	v_mul_f32_e32 v5, v4, v3
	v_fma_f32 v6, -v2, v5, v4
	v_fmac_f32_e32 v5, v6, v3
	v_fma_f32 v2, -v2, v5, v4
	v_div_fmas_f32 v2, v2, v3, v5
	v_div_fixup_f32 v1, v2, v1, 1.0
	ds_write_b32 v0, v1
.LBB0_1725:
	s_or_b64 exec, exec, s[10:11]
	s_cmp_lg_u32 s46, s46
	s_cselect_b64 s[0:1], -1, 0
	s_and_b64 s[0:1], s[0:1], s[4:5]
	s_and_saveexec_b64 s[10:11], s[0:1]
	s_cbranch_execz .LBB0_1727
	v_lshl_or_b32 v2, s46, 8, v197
	v_mov_b32_e32 v3, 0
	v_lshl_add_u64 v[4:5], v[2:3], 2, s[8:9]
	v_add_u32_e32 v6, 0x8000, v2
	v_mov_b32_e32 v7, v3
	v_add_u32_e32 v8, 0x10000, v2
	v_mov_b32_e32 v9, v3
	v_add_u32_e32 v10, 0x18000, v2
	v_mov_b32_e32 v11, v3
	v_add_u32_e32 v12, 0x20000, v2
	v_mov_b32_e32 v13, v3
	v_add_u32_e32 v14, 0x28000, v2
	v_mov_b32_e32 v15, v3
	v_add_u32_e32 v16, 0x30000, v2
	v_mov_b32_e32 v17, v3
	v_add_u32_e32 v18, 0x38000, v2
	v_mov_b32_e32 v19, v3
	v_lshl_add_u64 v[6:7], v[6:7], 2, s[8:9]
	v_lshl_add_u64 v[8:9], v[8:9], 2, s[8:9]
	v_lshl_add_u64 v[10:11], v[10:11], 2, s[8:9]
	v_lshl_add_u64 v[12:13], v[12:13], 2, s[8:9]
	v_lshl_add_u64 v[14:15], v[14:15], 2, s[8:9]
	v_lshl_add_u64 v[16:17], v[16:17], 2, s[8:9]
	v_lshl_add_u64 v[18:19], v[18:19], 2, s[8:9]
	global_load_dword v1, v[4:5], off
	global_load_dword v20, v[6:7], off
	global_load_dword v21, v[8:9], off
	global_load_dword v22, v[10:11], off
	global_load_dword v23, v[12:13], off
	global_load_dword v24, v[14:15], off
	global_load_dword v25, v[16:17], off
	global_load_dword v26, v[18:19], off
	v_add_u32_e32 v4, 0x40000, v2
	v_mov_b32_e32 v5, v3
	v_lshl_add_u64 v[4:5], v[4:5], 2, s[8:9]
	v_add_u32_e32 v6, 0x48000, v2
	v_mov_b32_e32 v7, v3
	v_add_u32_e32 v8, 0x50000, v2
	v_mov_b32_e32 v9, v3
	v_add_u32_e32 v10, 0x58000, v2
	v_mov_b32_e32 v11, v3
	v_add_u32_e32 v12, 0x60000, v2
	v_mov_b32_e32 v13, v3
	v_add_u32_e32 v14, 0x68000, v2
	v_mov_b32_e32 v15, v3
	v_add_u32_e32 v16, 0x70000, v2
	v_mov_b32_e32 v17, v3
	v_add_u32_e32 v2, 0x78000, v2
	v_lshl_add_u64 v[6:7], v[6:7], 2, s[8:9]
	v_lshl_add_u64 v[8:9], v[8:9], 2, s[8:9]
	v_lshl_add_u64 v[10:11], v[10:11], 2, s[8:9]
	v_lshl_add_u64 v[12:13], v[12:13], 2, s[8:9]
	v_lshl_add_u64 v[14:15], v[14:15], 2, s[8:9]
	v_lshl_add_u64 v[16:17], v[16:17], 2, s[8:9]
	v_lshl_add_u64 v[2:3], v[2:3], 2, s[8:9]
	global_load_dword v18, v[4:5], off
	global_load_dword v19, v[6:7], off
	global_load_dword v27, v[8:9], off
	global_load_dword v28, v[10:11], off
	global_load_dword v29, v[12:13], off
	global_load_dword v30, v[14:15], off
	global_load_dword v31, v[16:17], off
	global_load_dword v32, v[2:3], off
	v_mov_b32_e32 v2, 0x358637bd
	s_mov_b32 s0, 0xf800000
	v_mov_b32_e32 v3, 0x260
	s_waitcnt vmcnt(15)
	v_add_f32_e32 v1, 0, v1
	s_waitcnt vmcnt(14)
	v_add_f32_e32 v1, v1, v20
	s_waitcnt vmcnt(13)
	v_add_f32_e32 v1, v1, v21
	s_waitcnt vmcnt(12)
	v_add_f32_e32 v1, v1, v22
	s_waitcnt vmcnt(11)
	v_add_f32_e32 v1, v1, v23
	s_waitcnt vmcnt(10)
	v_add_f32_e32 v1, v1, v24
	s_waitcnt vmcnt(9)
	v_add_f32_e32 v1, v1, v25
	s_waitcnt vmcnt(8)
	v_add_f32_e32 v1, v1, v26
	s_waitcnt vmcnt(7)
	v_add_f32_e32 v1, v1, v18
	s_waitcnt vmcnt(6)
	v_add_f32_e32 v1, v1, v19
	s_waitcnt vmcnt(5)
	v_add_f32_e32 v1, v1, v27
	s_waitcnt vmcnt(4)
	v_add_f32_e32 v1, v1, v28
	s_waitcnt vmcnt(3)
	v_add_f32_e32 v1, v1, v29
	s_waitcnt vmcnt(2)
	v_add_f32_e32 v1, v1, v30
	s_waitcnt vmcnt(1)
	v_add_f32_e32 v1, v1, v31
	s_waitcnt vmcnt(0)
	v_add_f32_e32 v1, v1, v32
	v_fmac_f32_e32 v2, 0x3a800000, v1
	v_mul_f32_e32 v1, 0x4f800000, v2
	v_cmp_gt_f32_e32 vcc, s0, v2
	s_nop 1
	v_cndmask_b32_e32 v1, v2, v1, vcc
	v_sqrt_f32_e32 v2, v1
	s_nop 0
	v_add_u32_e32 v4, -1, v2
	v_add_u32_e32 v5, 1, v2
	v_fma_f32 v6, -v4, v2, v1
	v_fma_f32 v7, -v5, v2, v1
	v_cmp_ge_f32_e64 s[0:1], 0, v6
	s_nop 1
	v_cndmask_b32_e64 v2, v2, v4, s[0:1]
	v_cmp_lt_f32_e64 s[0:1], 0, v7
	s_nop 1
	v_cndmask_b32_e64 v2, v2, v5, s[0:1]
	v_mul_f32_e32 v4, 0x37800000, v2
	v_cndmask_b32_e32 v2, v2, v4, vcc
	v_cmp_class_f32_e32 vcc, v1, v3
	s_nop 1
	v_cndmask_b32_e32 v1, v2, v1, vcc
	v_div_scale_f32 v2, s[0:1], v1, v1, 1.0
	v_rcp_f32_e32 v3, v2
	v_div_scale_f32 v4, vcc, 1.0, v1, 1.0
	v_fma_f32 v5, -v2, v3, 1.0
	v_fmac_f32_e32 v3, v5, v3
	v_mul_f32_e32 v5, v4, v3
	v_fma_f32 v6, -v2, v5, v4
	v_fmac_f32_e32 v5, v6, v3
	v_fma_f32 v2, -v2, v5, v4
	v_div_fmas_f32 v2, v2, v3, v5
	v_div_fixup_f32 v1, v2, v1, 1.0
	ds_write_b32 v0, v1 offset:1024
